# mixer-prep: the 64 pool-weight dword loads issued in two batches with one wait each instead of 32 load-pair round trips (both layers)
# baseline (speedup 1.0000x reference)
; __device__ __forceinline__ unsigned pk2(float lo, float hi) { return pg8::cvt_pk_bf16(lo, hi); }
; __device__ __forceinline__ void phase_mixprep(const Params& P, int l, unsigned char* lds, int tid, int lane, int wave, int G, const int bid, const bool do_qk) {
;     ...
;         bf16x8 Wf[4][2];
; #pragma unroll
;         for (int nt = 0; nt < 4; ++nt)
; #pragma unroll
;             for (int ks = 0; ks < 2; ++ks) { const float* wp = P.pool_w + (size_t)((l * 4 + g) * 64 + 32 * ks + 8 * fq) * 64 + 16 * nt + fr;
;                 u32x4 w; w.x = pk2(wp[0], wp[64]); w.y = pk2(wp[128], wp[192]); w.z = pk2(wp[256], wp[320]); w.w = pk2(wp[384], wp[448]); Wf[nt][ks] = __builtin_bit_cast(bf16x8, w); }
;         f32x4 pscv[4];
; #pragma unroll
;         for (int nt = 0; nt < 4; ++nt) pscv[nt] = *(const f32x4*)(P.pool_scale + l * 256 + g * 64 + 16 * nt + 4 * fq);
;         const int nx = (NCHUNK > G && NCHUNK - G < G / 2) ? NCHUNK - G : 0, vb = bid - nx, GV = G - nx;
.LBB0_343:
	v_lshlrev_b32_e32 v0, 11, v187
	v_lshl_or_b32 v72, s53, 14, v0
	v_lshl_add_u64 v[0:1], s[36:37], 0, v[72:73]
	v_lshlrev_b32_e32 v72, 2, v184
	v_lshl_add_u64 v[28:29], v[0:1], 0, v[72:73]
	global_load_dword v96, v[28:29], off offset:256
	global_load_dword v97, v[28:29], off
	s_movk_i32 s2, 0x2000
	v_add_co_u32_e32 v30, vcc, s2, v28
	s_mov_b64 s[0:1], 0x2000
	s_nop 0
	v_addc_co_u32_e32 v31, vcc, 0, v29, vcc
	v_lshl_add_u64 v[8:9], v[28:29], 0, s[0:1]
	s_mov_b64 s[0:1], 0x2040
	v_lshl_add_u64 v[16:17], v[28:29], 0, s[0:1]
	s_mov_b64 s[0:1], 0x2080
	v_lshl_add_u64 v[24:25], v[28:29], 0, s[0:1]
	s_mov_b64 s[0:1], 0x20c0
	v_lshl_add_u64 v[32:33], v[28:29], 0, s[0:1]
	s_lshl_b32 s0, s54, 2
	s_add_u32 s0, s56, s0
	s_addc_u32 s1, s55, 0
	s_cmpk_lt_i32 s50, 0x104
	s_cselect_b64 s[8:9], -1, 0
	s_and_b64 vcc, exec, s[8:9]
	global_load_dword v98, v[28:29], off offset:768
	global_load_dword v99, v[28:29], off offset:512
	global_load_dword v100, v[28:29], off offset:1280
	global_load_dword v101, v[28:29], off offset:1024
	global_load_dword v102, v[28:29], off offset:1792
	global_load_dword v103, v[28:29], off offset:1536
	global_load_dword v104, v[30:31], off
	global_load_dword v105, v[8:9], off offset:256
	global_load_dword v106, v[8:9], off offset:768
	global_load_dword v107, v[8:9], off offset:512
	global_load_dword v108, v[8:9], off offset:1280
	global_load_dword v109, v[8:9], off offset:1024
	global_load_dword v110, v[8:9], off offset:1792
	global_load_dword v111, v[8:9], off offset:1536
	global_load_dword v112, v[28:29], off offset:320
	global_load_dword v113, v[28:29], off offset:64
	global_load_dword v114, v[28:29], off offset:832
	global_load_dword v115, v[28:29], off offset:576
	global_load_dword v116, v[28:29], off offset:1344
	global_load_dword v117, v[28:29], off offset:1088
	global_load_dword v118, v[28:29], off offset:1856
	global_load_dword v119, v[28:29], off offset:1600
	global_load_dword v120, v[30:31], off offset:64
	global_load_dword v121, v[16:17], off offset:256
	global_load_dword v122, v[16:17], off offset:768
	global_load_dword v123, v[16:17], off offset:512
	global_load_dword v124, v[16:17], off offset:1280
	global_load_dword v125, v[16:17], off offset:1024
	global_load_dword v126, v[16:17], off offset:1792
	global_load_dword v127, v[16:17], off offset:1536
	s_waitcnt vmcnt(0)
	global_load_dword v128, v[28:29], off offset:384
	global_load_dword v129, v[28:29], off offset:128
	global_load_dword v130, v[28:29], off offset:896
	global_load_dword v131, v[28:29], off offset:640
	global_load_dword v132, v[28:29], off offset:1408
	global_load_dword v133, v[28:29], off offset:1152
	global_load_dword v134, v[28:29], off offset:1920
	global_load_dword v135, v[28:29], off offset:1664
	global_load_dword v136, v[30:31], off offset:128
	global_load_dword v137, v[24:25], off offset:256
	global_load_dword v138, v[24:25], off offset:768
	global_load_dword v139, v[24:25], off offset:512
	global_load_dword v140, v[24:25], off offset:1280
	global_load_dword v141, v[24:25], off offset:1024
	global_load_dword v142, v[24:25], off offset:1792
	global_load_dword v143, v[24:25], off offset:1536
	global_load_dword v144, v[28:29], off offset:448
	global_load_dword v145, v[28:29], off offset:192
	global_load_dword v146, v[28:29], off offset:960
	global_load_dword v147, v[28:29], off offset:704
	global_load_dword v148, v[28:29], off offset:1472
	global_load_dword v149, v[28:29], off offset:1216
	global_load_dword v150, v[28:29], off offset:1984
	global_load_dword v151, v[28:29], off offset:1728
	global_load_dword v152, v[30:31], off offset:192
	global_load_dword v153, v[32:33], off offset:256
	global_load_dword v154, v[32:33], off offset:768
	global_load_dword v155, v[32:33], off offset:512
	global_load_dword v156, v[32:33], off offset:1280
	global_load_dword v157, v[32:33], off offset:1024
	global_load_dword v158, v[32:33], off offset:1792
	global_load_dword v159, v[32:33], off offset:1536
	s_waitcnt vmcnt(0)
	v_cvt_pk_bf16_f32 v0, v97, v96
	v_cvt_pk_bf16_f32 v1, v99, v98
	v_cvt_pk_bf16_f32 v2, v101, v100
	v_cvt_pk_bf16_f32 v3, v103, v102
	v_cvt_pk_bf16_f32 v4, v104, v105
	v_cvt_pk_bf16_f32 v5, v107, v106
	v_cvt_pk_bf16_f32 v6, v109, v108
	v_cvt_pk_bf16_f32 v7, v111, v110
	v_cvt_pk_bf16_f32 v8, v113, v112
	v_cvt_pk_bf16_f32 v9, v115, v114
	v_cvt_pk_bf16_f32 v10, v117, v116
	v_cvt_pk_bf16_f32 v11, v119, v118
	v_cvt_pk_bf16_f32 v12, v120, v121
	v_cvt_pk_bf16_f32 v13, v123, v122
	v_cvt_pk_bf16_f32 v14, v125, v124
	v_cvt_pk_bf16_f32 v15, v127, v126
	v_cvt_pk_bf16_f32 v16, v129, v128
	v_cvt_pk_bf16_f32 v17, v131, v130
	v_cvt_pk_bf16_f32 v18, v133, v132
	v_cvt_pk_bf16_f32 v19, v135, v134
	v_cvt_pk_bf16_f32 v20, v136, v137
	v_cvt_pk_bf16_f32 v21, v139, v138
	v_cvt_pk_bf16_f32 v22, v141, v140
	v_cvt_pk_bf16_f32 v23, v143, v142
	v_cvt_pk_bf16_f32 v24, v145, v144
	v_cvt_pk_bf16_f32 v25, v147, v146
	v_cvt_pk_bf16_f32 v26, v149, v148
	v_cvt_pk_bf16_f32 v27, v151, v150
	v_cvt_pk_bf16_f32 v28, v152, v153
	v_cvt_pk_bf16_f32 v29, v155, v154
	v_cvt_pk_bf16_f32 v30, v157, v156
	v_cvt_pk_bf16_f32 v31, v159, v158
	global_load_dwordx4 v[32:35], v70, s[0:1]
	global_load_dwordx4 v[36:39], v70, s[0:1] offset:64
	global_load_dwordx4 v[40:43], v70, s[0:1] offset:128
	global_load_dwordx4 v[44:47], v70, s[0:1] offset:192
	s_cbranch_vccz .LBB0_345
	s_lshr_b32 s1, s50, 31
	s_add_i32 s1, s50, s1
	s_sub_i32 s0, 0x104, s50
	s_ashr_i32 s1, s1, 1
	s_cmp_lt_i32 s0, s1
	s_cselect_b32 s52, s0, 0

; __device__ __forceinline__ unsigned pk2(float lo, float hi) { return pg8::cvt_pk_bf16(lo, hi); }
; __device__ __forceinline__ void phase_mixprep(const Params& P, int l, unsigned char* lds, int tid, int lane, int wave, int G, const int bid, const bool do_qk) {
;     ...
;         bf16x8 Wf[4][2];
; #pragma unroll
;         for (int nt = 0; nt < 4; ++nt)
; #pragma unroll
;             for (int ks = 0; ks < 2; ++ks) { const float* wp = P.pool_w + (size_t)((l * 4 + g) * 64 + 32 * ks + 8 * fq) * 64 + 16 * nt + fr;
;                 u32x4 w; w.x = pk2(wp[0], wp[64]); w.y = pk2(wp[128], wp[192]); w.z = pk2(wp[256], wp[320]); w.w = pk2(wp[384], wp[448]); Wf[nt][ks] = __builtin_bit_cast(bf16x8, w); }
;         f32x4 pscv[4];
; #pragma unroll
;         for (int nt = 0; nt < 4; ++nt) pscv[nt] = *(const f32x4*)(P.pool_scale + l * 256 + g * 64 + 16 * nt + 4 * fq);
;         const int nx = (NCHUNK > G && NCHUNK - G < G / 2) ? NCHUNK - G : 0, vb = bid - nx, GV = G - nx;
.LBB0_1245:
	v_lshlrev_b32_e32 v0, 11, v187
	v_lshl_or_b32 v72, s53, 14, v0
	v_lshl_add_u64 v[0:1], s[36:37], 0, v[72:73]
	v_lshlrev_b32_e32 v72, 2, v184
	v_lshl_add_u64 v[28:29], v[0:1], 0, v[72:73]
	v_add_co_u32_e32 v24, vcc, 0x10000, v28
	s_mov_b64 s[0:1], 0x10000
	s_nop 0
	v_addc_co_u32_e32 v25, vcc, 0, v29, vcc
	v_lshl_add_u64 v[4:5], v[28:29], 0, s[0:1]
	global_load_dword v96, v[24:25], off
	global_load_dword v97, v[4:5], off offset:256
	s_mov_b32 s2, 0x12000
	v_add_co_u32_e32 v30, vcc, s2, v28
	s_mov_b64 s[0:1], 0x12000
	s_nop 0
	v_addc_co_u32_e32 v31, vcc, 0, v29, vcc
	v_lshl_add_u64 v[8:9], v[28:29], 0, s[0:1]
	s_mov_b64 s[0:1], 0x10040
	v_lshl_add_u64 v[12:13], v[28:29], 0, s[0:1]
	s_mov_b64 s[0:1], 0x12040
	v_lshl_add_u64 v[16:17], v[28:29], 0, s[0:1]
	s_mov_b64 s[0:1], 0x10080
	v_lshl_add_u64 v[20:21], v[28:29], 0, s[0:1]
	s_mov_b64 s[0:1], 0x12080
	v_lshl_add_u64 v[26:27], v[28:29], 0, s[0:1]
	s_mov_b64 s[0:1], 0x100c0
	v_lshl_add_u64 v[32:33], v[28:29], 0, s[0:1]
	s_mov_b64 s[0:1], 0x120c0
	global_load_dword v98, v[4:5], off offset:768
	global_load_dword v99, v[4:5], off offset:512
	global_load_dword v100, v[4:5], off offset:1280
	global_load_dword v101, v[4:5], off offset:1024
	global_load_dword v102, v[4:5], off offset:1792
	global_load_dword v103, v[4:5], off offset:1536
	global_load_dword v104, v[30:31], off
	global_load_dword v105, v[8:9], off offset:256
	global_load_dword v106, v[8:9], off offset:768
	global_load_dword v107, v[8:9], off offset:512
	global_load_dword v108, v[8:9], off offset:1280
	global_load_dword v109, v[8:9], off offset:1024
	global_load_dword v110, v[8:9], off offset:1792
	global_load_dword v111, v[8:9], off offset:1536
	global_load_dword v112, v[24:25], off offset:64
	global_load_dword v113, v[12:13], off offset:256
	global_load_dword v114, v[12:13], off offset:768
	global_load_dword v115, v[12:13], off offset:512
	global_load_dword v116, v[12:13], off offset:1280
	global_load_dword v117, v[12:13], off offset:1024
	global_load_dword v118, v[12:13], off offset:1792
	global_load_dword v119, v[12:13], off offset:1536
	global_load_dword v120, v[30:31], off offset:64
	global_load_dword v121, v[16:17], off offset:256
	global_load_dword v122, v[16:17], off offset:768
	global_load_dword v123, v[16:17], off offset:512
	global_load_dword v124, v[16:17], off offset:1280
	global_load_dword v125, v[16:17], off offset:1024
	global_load_dword v126, v[16:17], off offset:1792
	global_load_dword v127, v[16:17], off offset:1536
	s_waitcnt vmcnt(0)
	global_load_dword v128, v[24:25], off offset:128
	global_load_dword v129, v[20:21], off offset:256
	global_load_dword v130, v[20:21], off offset:768
	global_load_dword v131, v[20:21], off offset:512
	global_load_dword v132, v[20:21], off offset:1280
	global_load_dword v133, v[20:21], off offset:1024
	global_load_dword v134, v[20:21], off offset:1792
	global_load_dword v135, v[20:21], off offset:1536
	global_load_dword v136, v[30:31], off offset:128
	global_load_dword v137, v[26:27], off offset:256
	global_load_dword v138, v[26:27], off offset:768
	global_load_dword v139, v[26:27], off offset:512
	global_load_dword v140, v[26:27], off offset:1280
	global_load_dword v141, v[26:27], off offset:1024
	global_load_dword v142, v[26:27], off offset:1792
	global_load_dword v143, v[26:27], off offset:1536
	global_load_dword v144, v[24:25], off offset:192
	global_load_dword v145, v[32:33], off offset:256
	global_load_dword v146, v[32:33], off offset:768
	global_load_dword v147, v[32:33], off offset:512
	global_load_dword v148, v[32:33], off offset:1280
	global_load_dword v149, v[32:33], off offset:1024
	global_load_dword v150, v[32:33], off offset:1792
	global_load_dword v151, v[32:33], off offset:1536
	v_lshl_add_u64 v[32:33], v[28:29], 0, s[0:1]
	s_lshl_b32 s0, s54, 2
	s_add_u32 s0, s56, s0
	s_addc_u32 s1, s55, 0
	s_cmpk_lt_i32 s50, 0x104
	s_cselect_b64 s[8:9], -1, 0
	s_and_b64 vcc, exec, s[8:9]
	global_load_dword v152, v[30:31], off offset:192
	global_load_dword v153, v[32:33], off offset:256
	global_load_dword v154, v[32:33], off offset:768
	global_load_dword v155, v[32:33], off offset:512
	global_load_dword v156, v[32:33], off offset:1280
	global_load_dword v157, v[32:33], off offset:1024
	global_load_dword v158, v[32:33], off offset:1792
	global_load_dword v159, v[32:33], off offset:1536
	s_waitcnt vmcnt(0)
	v_cvt_pk_bf16_f32 v0, v96, v97
	v_cvt_pk_bf16_f32 v1, v99, v98
	v_cvt_pk_bf16_f32 v2, v101, v100
	v_cvt_pk_bf16_f32 v3, v103, v102
	v_cvt_pk_bf16_f32 v4, v104, v105
	v_cvt_pk_bf16_f32 v5, v107, v106
	v_cvt_pk_bf16_f32 v6, v109, v108
	v_cvt_pk_bf16_f32 v7, v111, v110
	v_cvt_pk_bf16_f32 v8, v112, v113
	v_cvt_pk_bf16_f32 v9, v115, v114
	v_cvt_pk_bf16_f32 v10, v117, v116
	v_cvt_pk_bf16_f32 v11, v119, v118
	v_cvt_pk_bf16_f32 v12, v120, v121
	v_cvt_pk_bf16_f32 v13, v123, v122
	v_cvt_pk_bf16_f32 v14, v125, v124
	v_cvt_pk_bf16_f32 v15, v127, v126
	v_cvt_pk_bf16_f32 v16, v128, v129
	v_cvt_pk_bf16_f32 v17, v131, v130
	v_cvt_pk_bf16_f32 v18, v133, v132
	v_cvt_pk_bf16_f32 v19, v135, v134
	v_cvt_pk_bf16_f32 v20, v136, v137
	v_cvt_pk_bf16_f32 v21, v139, v138
	v_cvt_pk_bf16_f32 v22, v141, v140
	v_cvt_pk_bf16_f32 v23, v143, v142
	v_cvt_pk_bf16_f32 v24, v144, v145
	v_cvt_pk_bf16_f32 v25, v147, v146
	v_cvt_pk_bf16_f32 v26, v149, v148
	v_cvt_pk_bf16_f32 v27, v151, v150
	v_cvt_pk_bf16_f32 v28, v152, v153
	v_cvt_pk_bf16_f32 v29, v155, v154
	v_cvt_pk_bf16_f32 v30, v157, v156
	v_cvt_pk_bf16_f32 v31, v159, v158
	global_load_dwordx4 v[32:35], v70, s[0:1] offset:1024
	global_load_dwordx4 v[36:39], v70, s[0:1] offset:1088
	global_load_dwordx4 v[40:43], v70, s[0:1] offset:1152
	global_load_dwordx4 v[44:47], v70, s[0:1] offset:1216
	s_cbranch_vccz .LBB0_1247
	s_lshr_b32 s1, s50, 31
	s_add_i32 s1, s50, s1
	s_sub_i32 s0, 0x104, s50
	s_ashr_i32 s1, s1, 1
	s_cmp_lt_i32 s0, s1
	s_cselect_b32 s52, s0, 0
